# MLA loop: running 64-bit K/V/k_rope tile pointers (5 VALU) instead of recomputing addresses from the row counter (14 VALU + 4 s_nop); 0+x sum starts folded
# baseline (speedup 1.0000x reference)
.LBB0_555:
	s_lshl_b32 s2, s6, 4
	s_add_i32 s2, s7, s2
	s_ashr_i32 s3, s2, 4
	v_mov_b32_e32 v58, v163
	s_mul_i32 s2, s3, 0x1100
	v_readlane_b32 s4, v253, 36
	s_add_i32 s4, s4, s2
	v_and_b32_e32 v125, 15, v58
	v_ashrrev_i32_e32 v0, 1, v58
	v_bfe_u32 v59, v58, 4, 2
	v_and_b32_e32 v0, 0xffffffe0, v0
	s_waitcnt vmcnt(3)
	v_or_b32_e32 v2, s4, v125
	v_readlane_b32 s4, v254, 16
	v_add_u32_e32 v112, v2, v0
	v_lshlrev_b32_e32 v0, 4, v59
	v_readlane_b32 s5, v254, 17
	s_movk_i32 s8, 0xc00
	s_mulk_i32 s3, 0xef00
	v_lshl_add_u64 v[30:31], s[4:5], 0, v[0:1]
	s_waitcnt vmcnt(2)
	v_mad_i64_i32 v[6:7], s[4:5], v112, s8, v[30:31]
	s_waitcnt lgkmcnt(0)
	global_load_dwordx4 v[10:13], v[6:7], off offset:128
	s_addk_i32 s3, 0xff00
	v_add_u32_e32 v2, s3, v112
	v_ashrrev_i32_e32 v32, 6, v2
	v_and_b32_e32 v2, 47, v112
	v_cmp_gt_u32_e32 vcc, 2, v59
	v_readlane_b32 s40, v254, 55
	v_readlane_b32 s50, v255, 1
	v_cndmask_b32_e32 v2, v2, v32, vcc
	v_lshlrev_b32_e32 v2, 4, v2
	v_ashrrev_i32_e32 v3, 31, v2
	v_readlane_b32 s51, v255, 2
	v_cmp_lt_i32_e64 s[4:5], v198, v196
	v_or_b32_e32 v110, 16, v112
	v_lshl_add_u64 v[2:3], v[2:3], 2, s[50:51]
	global_load_dwordx4 v[14:17], v[2:3], off
	global_load_dwordx4 v[18:21], v[2:3], off offset:16
	global_load_dwordx4 v[22:25], v[2:3], off offset:32
	global_load_dwordx4 v[26:29], v[2:3], off offset:48
	v_cndmask_b32_e64 v2, v195, v198, s[4:5]
	v_mad_i64_i32 v[30:31], s[4:5], v110, s8, v[30:31]
	v_lshlrev_b32_e32 v124, 2, v2
	v_bitop3_b32 v33, v112, 63, 16 bitop3:0xc8
	global_load_dwordx4 v[2:5], v[6:7], off
	s_nop 0
	global_load_dwordx4 v[6:9], v[6:7], off offset:64
	v_cndmask_b32_e32 v32, v33, v32, vcc
	global_load_dwordx4 v[42:45], v[30:31], off offset:128
	v_lshlrev_b32_e32 v32, 4, v32
	v_ashrrev_i32_e32 v33, 31, v32
	v_lshl_add_u64 v[32:33], v[32:33], 2, s[50:51]
	global_load_dwordx4 v[38:41], v[32:33], off offset:48
	global_load_dwordx4 v[46:49], v[32:33], off offset:32
	global_load_dwordx4 v[50:53], v[32:33], off offset:16
	global_load_dwordx4 v[54:57], v[32:33], off
	v_and_b32_e32 v68, 16, v58
	v_cmp_eq_u32_e32 vcc, 0, v68
	v_ashrrev_i32_e32 v126, 3, v58
	v_readlane_b32 s4, v254, 18
	v_readlane_b32 s5, v254, 19
	v_readlane_b32 s8, v254, 36
	v_mov_b32_e32 v115, v1
	v_readlane_b32 s9, v254, 37
	v_ashrrev_i32_e32 v128, 2, v58
	v_readlane_b32 s41, v254, 56
	v_readlane_b32 s42, v254, 57
	v_readlane_b32 s43, v254, 58
	v_readlane_b32 s44, v254, 59
	v_readlane_b32 s45, v254, 60
	v_readlane_b32 s46, v254, 61
	v_readlane_b32 s47, v254, 62
	v_readlane_b32 s48, v254, 63
	v_readlane_b32 s49, v255, 0
	v_readlane_b32 s52, v255, 3
	v_readlane_b32 s53, v255, 4
	v_readlane_b32 s54, v255, 5
	v_readlane_b32 s55, v255, 6
	v_readlane_b32 s40, v252, 16
	v_readlane_b32 s42, v252, 18
	v_readlane_b32 s43, v252, 19
	v_mov_b32_e32 v117, v1
	s_waitcnt vmcnt(12)
	v_lshlrev_b32_e32 v131, 2, v59
	v_ashrrev_i32_e32 v113, 31, v112
	v_ashrrev_i32_e32 v111, 31, v110
	v_mov_b32_e32 v140, 0
	v_mov_b32_e32 v138, 0xf149f2ca
	v_mov_b32_e32 v139, 0xf149f2ca
	v_mov_b32_e32 v141, 0
	v_readlane_b32 s41, v252, 17
	v_readlane_b32 s44, v252, 20
	v_readlane_b32 s45, v252, 21
	v_readlane_b32 s46, v252, 22
	v_readlane_b32 s47, v252, 23
	v_readlane_b32 s48, v252, 24
	v_readlane_b32 s49, v252, 25
	v_readlane_b32 s50, v252, 26
	v_readlane_b32 s51, v252, 27
	v_readlane_b32 s52, v252, 28
	v_readlane_b32 s53, v252, 29
	v_readlane_b32 s54, v252, 30
	v_readlane_b32 s55, v252, 31
	s_waitcnt vmcnt(11)
	v_and_b32_e32 v33, 0xffff0000, v10
	v_lshlrev_b32_e32 v32, 16, v10
	v_and_b32_e32 v35, 0xffff0000, v11
	v_lshlrev_b32_e32 v34, 16, v11
	v_and_b32_e32 v11, 0xffff0000, v12
	v_lshlrev_b32_e32 v10, 16, v12
	v_and_b32_e32 v37, 0xffff0000, v13
	v_lshlrev_b32_e32 v36, 16, v13
	ds_bpermute_b32 v12, v124, v32
	ds_bpermute_b32 v13, v124, v33
	ds_bpermute_b32 v60, v124, v34
	ds_bpermute_b32 v61, v124, v35
	ds_bpermute_b32 v62, v124, v10
	ds_bpermute_b32 v63, v124, v11
	s_waitcnt vmcnt(10)
	v_mov_b32_e32 v67, v16
	v_mov_b32_e32 v16, v15
	s_waitcnt vmcnt(9)
	v_mov_b32_e32 v15, v20
	v_mov_b32_e32 v20, v19
	s_waitcnt vmcnt(8)
	v_mov_b32_e32 v19, v24
	v_mov_b32_e32 v24, v23
	s_waitcnt lgkmcnt(4)
	v_pk_mul_f32 v[12:13], v[16:17], v[12:13]
	s_waitcnt lgkmcnt(2)
	v_pk_mul_f32 v[16:17], v[20:21], v[60:61]
	ds_bpermute_b32 v64, v124, v36
	ds_bpermute_b32 v65, v124, v37
	v_mov_b32_e32 v66, v14
	v_mov_b32_e32 v14, v18
	s_waitcnt lgkmcnt(2)
	v_pk_mul_f32 v[20:21], v[24:25], v[62:63]
	v_cndmask_b32_e64 v17, v17, -v17, vcc
	v_cndmask_b32_e64 v16, v16, -v16, vcc
	v_mov_b32_e32 v18, v22
	v_cndmask_b32_e64 v13, v13, -v13, vcc
	v_cndmask_b32_e64 v12, v12, -v12, vcc
	v_cndmask_b32_e64 v21, v21, -v21, vcc
	v_cndmask_b32_e64 v20, v20, -v20, vcc
	v_pk_fma_f32 v[14:15], v[14:15], v[34:35], v[16:17]
	v_pk_fma_f32 v[12:13], v[66:67], v[32:33], v[12:13]
	v_pk_fma_f32 v[10:11], v[18:19], v[10:11], v[20:21]
	v_add_u32_e32 v60, s2, v126
	v_mov_b32_e32 v75, v15
	v_ashrrev_i32_e32 v61, 31, v60
	v_add_u32_e32 v18, 0x200, v58
	s_waitcnt vmcnt(7)
	v_mov_b32_e32 v23, v28
	v_mov_b32_e32 v28, v27
	v_mov_b32_e32 v72, v12
	v_mov_b32_e32 v74, v14
	v_lshlrev_b64 v[14:15], 11, v[60:61]
	v_lshlrev_b32_e32 v12, 4, v58
	v_ashrrev_i32_e32 v127, 3, v18
	s_waitcnt lgkmcnt(0)
	v_pk_mul_f32 v[24:25], v[28:29], v[64:65]
	v_mov_b32_e32 v76, v10
	v_mov_b32_e32 v77, v11
	v_lshl_add_u64 v[10:11], s[4:5], 0, v[14:15]
	v_and_b32_e32 v114, 0x70, v12
	v_add_u32_e32 v62, s2, v127
	v_mov_b32_e32 v22, v26
	v_cndmask_b32_e64 v25, v25, -v25, vcc
	v_cndmask_b32_e64 v24, v24, -v24, vcc
	v_lshl_add_u64 v[10:11], v[10:11], 0, v[114:115]
	v_lshl_add_u64 v[14:15], s[8:9], 0, v[14:15]
	v_ashrrev_i32_e32 v63, 31, v62
	v_pk_fma_f32 v[26:27], v[22:23], v[36:37], v[24:25]
	v_mov_b32_e32 v73, v13
	global_load_dwordx4 v[10:13], v[10:11], off
	v_lshl_add_u64 v[14:15], v[14:15], 0, v[114:115]
	v_lshlrev_b64 v[22:23], 11, v[62:63]
	v_add_u32_e32 v64, s2, v128
	v_lshlrev_b32_e32 v34, 3, v58
	global_load_dwordx4 v[14:17], v[14:15], off
	v_lshl_add_u64 v[18:19], s[4:5], 0, v[22:23]
	v_ashrrev_i32_e32 v65, 31, v64
	v_lshl_add_u64 v[18:19], v[18:19], 0, v[114:115]
	v_lshl_add_u64 v[22:23], s[8:9], 0, v[22:23]
	v_lshlrev_b64 v[28:29], 6, v[64:65]
	v_and_b32_e32 v130, 24, v34
	global_load_dwordx4 v[18:21], v[18:19], off
	v_lshl_add_u64 v[22:23], v[22:23], 0, v[114:115]
	v_lshl_add_u64 v[28:29], s[42:43], 0, v[28:29]
	v_lshlrev_b32_e32 v116, 1, v130
	global_load_dwordx4 v[22:25], v[22:23], off
	v_lshl_add_u64 v[28:29], v[28:29], 0, v[116:117]
	global_load_dwordx4 v[34:37], v[28:29], off
	v_mov_b32_e32 v61, v26
	v_mov_b32_e32 v63, v27
	global_load_dwordx4 v[26:29], v[30:31], off
	s_nop 0
	global_load_dwordx4 v[30:33], v[30:31], off offset:64
	s_waitcnt vmcnt(11)
	v_and_b32_e32 v67, 0xffff0000, v42
	v_lshlrev_b32_e32 v66, 16, v42
	ds_bpermute_b32 v68, v124, v66
	ds_bpermute_b32 v69, v124, v67
	s_waitcnt vmcnt(7)
	v_mov_b32_e32 v71, v56
	v_mov_b32_e32 v56, v55
	v_mov_b32_e32 v70, v54
	v_lshl_add_u64 v[118:119], s[4:5], 0, v[114:115]
	s_waitcnt lgkmcnt(0)
	v_pk_mul_f32 v[54:55], v[56:57], v[68:69]
	v_and_b32_e32 v57, 0xffff0000, v43
	v_lshlrev_b32_e32 v56, 16, v43
	ds_bpermute_b32 v42, v124, v56
	ds_bpermute_b32 v43, v124, v57
	v_cndmask_b32_e64 v55, v55, -v55, vcc
	v_cndmask_b32_e64 v54, v54, -v54, vcc
	v_pk_fma_f32 v[54:55], v[70:71], v[66:67], v[54:55]
	v_mov_b32_e32 v66, v50
	v_mov_b32_e32 v67, v52
	v_mov_b32_e32 v52, v51
	v_and_b32_e32 v51, 0xffff0000, v44
	v_lshlrev_b32_e32 v50, 16, v44
	s_waitcnt lgkmcnt(0)
	v_pk_mul_f32 v[42:43], v[52:53], v[42:43]
	ds_bpermute_b32 v52, v124, v50
	ds_bpermute_b32 v53, v124, v51
	v_cndmask_b32_e64 v43, v43, -v43, vcc
	v_cndmask_b32_e64 v42, v42, -v42, vcc
	v_pk_fma_f32 v[42:43], v[66:67], v[56:57], v[42:43]
	v_mov_b32_e32 v57, v48
	v_mov_b32_e32 v48, v47
	v_mov_b32_e32 v56, v46
	s_waitcnt lgkmcnt(0)
	v_pk_mul_f32 v[46:47], v[48:49], v[52:53]
	v_and_b32_e32 v49, 0xffff0000, v45
	v_lshlrev_b32_e32 v48, 16, v45
	ds_bpermute_b32 v44, v124, v48
	ds_bpermute_b32 v45, v124, v49
	v_cndmask_b32_e64 v47, v47, -v47, vcc
	v_cndmask_b32_e64 v46, v46, -v46, vcc
	v_pk_fma_f32 v[46:47], v[56:57], v[50:51], v[46:47]
	v_mov_b32_e32 v51, v40
	v_mov_b32_e32 v40, v39
	v_mov_b32_e32 v50, v38
	s_waitcnt lgkmcnt(0)
	v_pk_mul_f32 v[38:39], v[40:41], v[44:45]
	v_cndmask_b32_e64 v39, v39, -v39, vcc
	v_cndmask_b32_e64 v38, v38, -v38, vcc
	v_pk_fma_f32 v[38:39], v[50:51], v[48:49], v[38:39]
	v_mov_b32_e32 v44, v47
	v_mov_b32_e32 v45, v38
	v_mov_b32_e32 v47, v39
	v_mad_u64_u32 v[38:39], s[2:3], v126, s12, v[114:115]
	v_lshlrev_b32_e32 v39, 6, v126
	s_waitcnt vmcnt(6)
	ds_write_b128 v38, v[10:13]
	v_sub_u32_e32 v38, v38, v39
	v_cmp_lt_i32_e32 vcc, v197, v196
	s_waitcnt vmcnt(5)
	ds_write_b128 v38, v[14:17] offset:53248
	v_mad_u64_u32 v[38:39], s[2:3], v127, s12, v[114:115]
	v_lshlrev_b32_e32 v39, 6, v127
	s_waitcnt vmcnt(4)
	ds_write_b128 v38, v[18:21]
	v_sub_u32_e32 v38, v38, v39
	s_waitcnt vmcnt(3)
	ds_write_b128 v38, v[22:25] offset:53248
	v_mad_u64_u32 v[38:39], s[2:3], v128, s12, v[116:117]
	s_waitcnt vmcnt(2)
	ds_write_b128 v38, v[34:37] offset:128
	v_cndmask_b32_e32 v38, v195, v197, vcc
	v_lshlrev_b32_e32 v129, 2, v38
	v_bfe_u32 v38, v58, 2, 2
	v_mov_b32_e32 v48, v1
	v_mov_b32_e32 v49, v1
	v_or_b32_e32 v132, v131, v38
	v_cvt_pk_bf16_f32 v41, v61, v63
	v_cvt_pk_bf16_f32 v40, v76, v77
	v_cvt_pk_bf16_f32 v39, v74, v75
	v_cvt_pk_bf16_f32 v38, v72, v73
	v_cvt_pk_bf16_f32 v45, v45, v47
	v_cvt_pk_bf16_f32 v44, v46, v44
	v_cvt_pk_bf16_f32 v43, v42, v43
	v_cvt_pk_bf16_f32 v42, v54, v55
	v_lshl_add_u64 v[120:121], s[8:9], 0, v[114:115]
	v_lshl_add_u64 v[122:123], s[42:43], 0, v[116:117]
	v_add_u32_e32 v115, 0x80, v64
	v_add_u32_e32 v117, 0x80, v62
	v_add_u32_e32 v137, 0x80, v60
	s_mov_b32 s100, 0x40000
	s_mov_b32 s101, 0
	v_mov_b32_e32 v242, 0x2000
	v_mov_b32_e32 v243, 0
	v_mov_b32_e32 v240, v137
	v_ashrrev_i32_e32 v241, 31, v137
	v_lshlrev_b64 v[240:241], 11, v[240:241]
	v_lshl_add_u64 v[232:233], v[118:119], 0, v[240:241]
	v_lshl_add_u64 v[234:235], v[120:121], 0, v[240:241]
	v_mov_b32_e32 v240, v117
	v_ashrrev_i32_e32 v241, 31, v117
	v_lshlrev_b64 v[240:241], 11, v[240:241]
	v_lshl_add_u64 v[236:237], v[118:119], 0, v[240:241]
	v_lshl_add_u64 v[238:239], v[120:121], 0, v[240:241]
	v_mov_b32_e32 v240, v115
	v_ashrrev_i32_e32 v241, 31, v115
	v_lshlrev_b64 v[240:241], 6, v[240:241]
	v_lshl_add_u64 v[244:245], v[122:123], 0, v[240:241]
	v_mov_b32_e32 v46, v1
	v_mov_b32_e32 v47, v1
	v_mov_b64_e32 v[64:65], v[48:49]
	v_mov_b64_e32 v[52:53], v[48:49]
	v_mov_b64_e32 v[68:69], v[48:49]
	v_mov_b64_e32 v[56:57], v[48:49]
	v_mov_b64_e32 v[72:73], v[48:49]
	v_mov_b64_e32 v[60:61], v[48:49]
	v_mov_b64_e32 v[76:77], v[48:49]
	v_or_b32_e32 v133, 0xd000, v130
	v_or_b32_e32 v134, 0xd020, v130
	v_or_b32_e32 v135, 0xd040, v130
	v_or_b32_e32 v136, 0xd060, v130
	s_mov_b32 s4, 0
	v_mov_b64_e32 v[62:63], v[46:47]
	v_mov_b64_e32 v[50:51], v[46:47]
	v_mov_b64_e32 v[66:67], v[46:47]
	v_mov_b64_e32 v[54:55], v[46:47]
	v_mov_b64_e32 v[70:71], v[46:47]
	v_mov_b64_e32 v[58:59], v[46:47]
	v_mov_b64_e32 v[74:75], v[46:47]
	v_mad_u32_u24 v224, v126, s12, v114
	v_mad_u32_u24 v225, v126, s16, v114
	v_mad_u32_u24 v226, v127, s12, v114
	v_mad_u32_u24 v227, v127, s16, v114
	v_mad_u32_u24 v228, v128, s12, v116
	v_add_u32_e32 v229, 0x4800, v225
	v_add_u32_e32 v230, 0x4800, v227
	s_waitcnt vmcnt(0)
	s_waitcnt lgkmcnt(0)
	s_barrier
	s_branch .LBB0_557
.LBB0_556:
	v_add_f32_e32 v90, v91, v90
	v_add_f32_e32 v90, v92, v90
	v_add_f32_e32 v90, v93, v90
	v_add_f32_e32 v82, v82, v90
	v_add_f32_e32 v82, v83, v82
	v_add_f32_e32 v82, v84, v82
	v_add_f32_e32 v82, v85, v82
	v_add_f32_e32 v82, v86, v82
	v_add_f32_e32 v82, v87, v82
	v_add_f32_e32 v82, v88, v82
	v_add_f32_e32 v82, v89, v82
	v_add_f32_e32 v78, v78, v82
	v_add_f32_e32 v78, v79, v78
	v_add_f32_e32 v78, v80, v78
	v_add_f32_e32 v78, v81, v78
	v_add_f32_e32 v140, v140, v78
	v_add_f32_e32 v78, v107, v106
	v_add_f32_e32 v78, v108, v78
	v_add_f32_e32 v78, v109, v78
	v_add_f32_e32 v78, v98, v78
	v_add_f32_e32 v78, v99, v78
	v_add_f32_e32 v78, v100, v78
	v_add_f32_e32 v78, v101, v78
	v_add_f32_e32 v78, v102, v78
	v_add_f32_e32 v78, v103, v78
	v_add_f32_e32 v78, v104, v78
	v_add_f32_e32 v78, v105, v78
	v_add_f32_e32 v78, v94, v78
	v_add_f32_e32 v78, v95, v78
	v_add_f32_e32 v78, v96, v78
	v_add_f32_e32 v78, v97, v78
	s_addk_i32 s4, 0x80
	v_add_f32_e32 v141, v141, v78
	s_cmpk_lg_i32 s4, 0x1100
	s_waitcnt lgkmcnt(0)
	s_barrier
	s_cbranch_scc0 .LBB0_554
.LBB0_557:
	s_cmpk_lg_i32 s4, 0x1080
	s_cselect_b64 s[2:3], -1, 0
	s_cmpk_eq_i32 s4, 0x1080
	s_cbranch_scc1 .LBB0_559
	global_load_dwordx4 v[10:13], v[232:233], off
	global_load_dwordx4 v[14:17], v[234:235], off
	global_load_dwordx4 v[18:21], v[236:237], off
	global_load_dwordx4 v[22:25], v[238:239], off
	global_load_dwordx4 v[34:37], v[244:245], off
	v_lshl_add_u64 v[232:233], s[100:101], 0, v[232:233]
	v_lshl_add_u64 v[234:235], s[100:101], 0, v[234:235]
	v_lshl_add_u64 v[236:237], s[100:101], 0, v[236:237]
	v_lshl_add_u64 v[238:239], s[100:101], 0, v[238:239]
	v_lshl_add_u64 v[244:245], v[242:243], 0, v[244:245]

.LBB0_563:
	v_fma_f32 v106, v106, s21, -v139
	v_exp_f32_e32 v106, v106
	v_fma_f32 v107, v107, s21, -v139
	v_exp_f32_e32 v107, v107
	v_fma_f32 v108, v108, s21, -v139
	v_exp_f32_e32 v108, v108
	v_fma_f32 v109, v109, s21, -v139
	v_exp_f32_e32 v109, v109
	v_fma_f32 v102, v102, s21, -v139
	v_mul_u32_u24_e32 v160, 0xd0, v142
	v_exp_f32_e32 v102, v102
	v_fma_f32 v103, v103, s21, -v139
	v_add_f32_e32 v142, v107, v106
	v_exp_f32_e32 v103, v103
	v_fma_f32 v104, v104, s21, -v139
	v_add_f32_e32 v142, v108, v142
	v_exp_f32_e32 v104, v104
	v_fma_f32 v105, v105, s21, -v139
	v_add_f32_e32 v142, v109, v142
	v_exp_f32_e32 v105, v105
	v_fma_f32 v98, v98, s21, -v139
	v_cvt_pk_bf16_f32 v106, v106, v107
	v_cvt_pk_bf16_f32 v107, v108, v109
	v_add_f32_e32 v108, v102, v142
	v_exp_f32_e32 v98, v98
	v_fma_f32 v99, v99, s21, -v139
	v_add_f32_e32 v108, v103, v108
	v_exp_f32_e32 v99, v99
	v_fma_f32 v100, v100, s21, -v139
	v_add_f32_e32 v108, v104, v108
	v_exp_f32_e32 v100, v100
	v_fma_f32 v101, v101, s21, -v139
	v_add_f32_e32 v142, v105, v108
	v_exp_f32_e32 v101, v101
	v_fma_f32 v94, v94, s21, -v139
	v_cvt_pk_bf16_f32 v108, v102, v103
	v_add_f32_e32 v102, v98, v142
	v_exp_f32_e32 v94, v94
	v_fma_f32 v95, v95, s21, -v139
	v_add_f32_e32 v102, v99, v102
	v_exp_f32_e32 v95, v95
	v_fma_f32 v96, v96, s21, -v139
	v_add_f32_e32 v102, v100, v102
	v_exp_f32_e32 v96, v96
	v_fma_f32 v97, v97, s21, -v139
	v_add_f32_e32 v102, v101, v102
	v_exp_f32_e32 v97, v97
	v_cvt_pk_bf16_f32 v98, v98, v99
	v_cvt_pk_bf16_f32 v99, v100, v101
	v_add_f32_e32 v100, v94, v102
	v_add_f32_e32 v100, v95, v100
	v_add_f32_e32 v100, v96, v100
	v_fma_f32 v90, v90, s21, -v138
	v_fma_f32 v86, v86, s21, -v138
	v_fma_f32 v78, v78, s21, -v138
	v_add_f32_e32 v102, v97, v100
	v_cvt_pk_bf16_f32 v100, v94, v95
	v_or_b32_e32 v94, s5, v132
	v_exp_f32_e32 v144, v90
	v_fma_f32 v90, v91, s21, -v138
	v_exp_f32_e32 v159, v86
	v_fma_f32 v86, v87, s21, -v138
	v_exp_f32_e32 v154, v78
	v_fma_f32 v78, v79, s21, -v138
	v_exp_f32_e32 v145, v90
	v_fma_f32 v90, v92, s21, -v138
	v_exp_f32_e32 v146, v86
	v_fma_f32 v86, v88, s21, -v138
	v_exp_f32_e32 v151, v78
	v_fma_f32 v78, v80, s21, -v138
	v_mul_u32_u24_e32 v143, 0x48, v94
	v_exp_f32_e32 v147, v90
	v_fma_f32 v90, v93, s21, -v138
	v_exp_f32_e32 v148, v86
	v_fma_f32 v86, v89, s21, -v138
	v_exp_f32_e32 v152, v78
	v_fma_f32 v78, v81, s21, -v138
	v_lshl_add_u32 v142, v143, 1, v130
	v_cvt_pk_bf16_f32 v101, v96, v97
	v_exp_f32_e32 v149, v90
	v_exp_f32_e32 v150, v86
	v_exp_f32_e32 v155, v78
	ds_read_b64_tr_b16 v[80:81], v142 offset:55552
	ds_read_b64_tr_b16 v[78:79], v142 offset:53248
	ds_read_b64_tr_b16 v[88:89], v142 offset:55584
	ds_read_b64_tr_b16 v[86:87], v142 offset:53280
	ds_read_b64_tr_b16 v[90:91], v142 offset:57856
	ds_read_b64_tr_b16 v[92:93], v142 offset:60160
	ds_read_b64_tr_b16 v[96:97], v142 offset:60192
	ds_read_b64_tr_b16 v[94:95], v142 offset:57888
	v_fma_f32 v82, v82, s21, -v138
	v_exp_f32_e32 v153, v82
	v_fma_f32 v82, v83, s21, -v138
	v_exp_f32_e32 v156, v82
	v_fma_f32 v82, v84, s21, -v138
	v_exp_f32_e32 v157, v82
	v_fma_f32 v82, v85, s21, -v138
	v_exp_f32_e32 v158, v82
	v_cvt_pk_bf16_f32 v109, v104, v105
	v_add_f32_e32 v141, v141, v102
	v_cvt_pk_bf16_f32 v82, v144, v145
	v_cvt_pk_bf16_f32 v83, v147, v149
	v_cvt_pk_bf16_f32 v84, v153, v156
	v_cvt_pk_bf16_f32 v85, v157, v158
	v_cvt_pk_bf16_f32 v102, v159, v146
	v_cvt_pk_bf16_f32 v103, v148, v150
	v_cvt_pk_bf16_f32 v104, v154, v151
	v_cvt_pk_bf16_f32 v105, v152, v155
	s_setprio 1
	s_waitcnt lgkmcnt(6)
	v_mfma_f32_16x16x32_bf16 v[74:77], v[78:81], v[106:109], v[74:77]
	v_mfma_f32_16x16x32_bf16 v[58:61], v[78:81], v[82:85], v[58:61]
	s_waitcnt lgkmcnt(4)
	v_mfma_f32_16x16x32_bf16 v[70:73], v[86:89], v[106:109], v[70:73]
	v_mfma_f32_16x16x32_bf16 v[78:81], v[86:89], v[82:85], v[54:57]
	s_waitcnt lgkmcnt(2)
	v_mfma_f32_16x16x32_bf16 v[74:77], v[90:93], v[98:101], v[74:77]
	v_mfma_f32_16x16x32_bf16 v[58:61], v[90:93], v[102:105], v[58:61]
	s_waitcnt lgkmcnt(0)
	v_mfma_f32_16x16x32_bf16 v[54:57], v[94:97], v[98:101], v[70:73]
	v_mfma_f32_16x16x32_bf16 v[70:73], v[94:97], v[102:105], v[78:81]
	s_setprio 0
	s_nop 1
	ds_read_b64_tr_b16 v[80:81], v142 offset:55616
	ds_read_b64_tr_b16 v[78:79], v142 offset:53312
	ds_read_b64_tr_b16 v[88:89], v142 offset:55648
	ds_read_b64_tr_b16 v[86:87], v142 offset:53344
	ds_read_b64_tr_b16 v[90:91], v142 offset:57920
	ds_read_b64_tr_b16 v[92:93], v142 offset:60224
	ds_read_b64_tr_b16 v[96:97], v142 offset:60256
	ds_read_b64_tr_b16 v[94:95], v142 offset:57952
	s_setprio 1
	s_waitcnt lgkmcnt(6)
	v_mfma_f32_16x16x32_bf16 v[66:69], v[78:81], v[106:109], v[66:69]
	v_mfma_f32_16x16x32_bf16 v[78:81], v[78:81], v[82:85], v[50:53]
	s_waitcnt lgkmcnt(2)
	v_mfma_f32_16x16x32_bf16 v[50:53], v[90:93], v[98:101], v[66:69]
	v_mfma_f32_16x16x32_bf16 v[66:69], v[90:93], v[102:105], v[78:81]
	v_mfma_f32_16x16x32_bf16 v[62:65], v[86:89], v[106:109], v[62:65]
	v_mfma_f32_16x16x32_bf16 v[78:81], v[86:89], v[82:85], v[46:49]
	s_waitcnt lgkmcnt(0)
	v_mfma_f32_16x16x32_bf16 v[46:49], v[94:97], v[98:101], v[62:65]
	v_mfma_f32_16x16x32_bf16 v[62:65], v[94:97], v[102:105], v[78:81]
	s_setprio 0
	v_add_u32_e32 v160, v0, v160
	s_nop 2
	ds_read_b128 v[78:81], v160 offset:13312
	ds_read_b128 v[82:85], v160 offset:13376
	ds_read_b128 v[86:89], v160 offset:13440
	ds_read_b128 v[94:97], v160 offset:16640
	ds_read_b128 v[98:101], v160 offset:16704
	ds_read_b128 v[102:105], v160 offset:16768
	s_setprio 1
	s_waitcnt lgkmcnt(5)
	v_mfma_f32_16x16x32_bf16 v[90:93], v[78:81], v[2:5], 0
	v_mfma_f32_16x16x32_bf16 v[78:81], v[78:81], v[26:29], 0
	s_waitcnt lgkmcnt(4)
	v_mfma_f32_16x16x32_bf16 v[90:93], v[82:85], v[6:9], v[90:93]
	v_mfma_f32_16x16x32_bf16 v[78:81], v[82:85], v[30:33], v[78:81]
	s_waitcnt lgkmcnt(3)
	v_mfma_f32_16x16x32_bf16 v[106:109], v[86:89], v[38:41], v[90:93]
	v_mfma_f32_16x16x32_bf16 v[90:93], v[86:89], v[42:45], v[78:81]
	s_waitcnt lgkmcnt(2)
	v_mfma_f32_16x16x32_bf16 v[78:81], v[94:97], v[2:5], 0
	v_mfma_f32_16x16x32_bf16 v[82:85], v[94:97], v[26:29], 0
	s_waitcnt lgkmcnt(1)
	v_mfma_f32_16x16x32_bf16 v[78:81], v[98:101], v[6:9], v[78:81]
	v_mfma_f32_16x16x32_bf16 v[82:85], v[98:101], v[30:33], v[82:85]
	s_waitcnt lgkmcnt(0)
	v_mfma_f32_16x16x32_bf16 v[98:101], v[102:105], v[38:41], v[78:81]
	v_mfma_f32_16x16x32_bf16 v[82:85], v[102:105], v[42:45], v[82:85]
	s_setprio 0
	s_nop 2
	ds_read_b128 v[78:81], v160 offset:19968
	ds_read_b128 v[86:89], v160 offset:20032
	ds_read_b128 v[94:97], v160 offset:20096
	ds_read_b128 v[164:167], v160 offset:23296
	ds_read_b128 v[168:171], v160 offset:23360
	ds_read_b128 v[172:175], v160 offset:23424
	s_setprio 1
	s_waitcnt lgkmcnt(5)
	v_mfma_f32_16x16x32_bf16 v[102:105], v[78:81], v[2:5], 0
	v_mfma_f32_16x16x32_bf16 v[78:81], v[78:81], v[26:29], 0
	s_waitcnt lgkmcnt(4)
	v_mfma_f32_16x16x32_bf16 v[102:105], v[86:89], v[6:9], v[102:105]
	v_mfma_f32_16x16x32_bf16 v[78:81], v[86:89], v[30:33], v[78:81]
	s_waitcnt lgkmcnt(3)
	v_mfma_f32_16x16x32_bf16 v[102:105], v[94:97], v[38:41], v[102:105]
	v_mfma_f32_16x16x32_bf16 v[86:89], v[94:97], v[42:45], v[78:81]
	s_waitcnt lgkmcnt(2)
	v_mfma_f32_16x16x32_bf16 v[78:81], v[164:167], v[2:5], 0
	v_mfma_f32_16x16x32_bf16 v[94:97], v[164:167], v[26:29], 0
	s_waitcnt lgkmcnt(1)
	v_mfma_f32_16x16x32_bf16 v[78:81], v[168:171], v[6:9], v[78:81]
	v_mfma_f32_16x16x32_bf16 v[164:167], v[168:171], v[30:33], v[94:97]
	s_waitcnt lgkmcnt(0)
	v_mfma_f32_16x16x32_bf16 v[94:97], v[172:175], v[38:41], v[78:81]
	v_mfma_f32_16x16x32_bf16 v[78:81], v[172:175], v[42:45], v[164:167]
	s_setprio 0
	v_max3_f32 v160, v106, s18, v107
	v_max3_f32 v160, v160, v108, v109
	v_max3_f32 v160, v160, v98, v99
	v_max3_f32 v160, v160, v100, v101
	v_max3_f32 v160, v160, v102, v103
	v_max3_f32 v160, v160, v104, v105
	v_max3_f32 v160, v160, v94, v95
	v_max3_f32 v160, v160, v96, v97
	v_mul_f32_e32 v160, 0x3e16c740, v160
	v_mov_b32_e32 v161, v160
	s_nop 1
	v_permlane16_swap_b32_e32 v161, v160
	v_max_f32_e32 v160, v160, v161
	v_mov_b32_e32 v161, v160
	s_nop 1
	v_permlane32_swap_b32_e32 v161, v160
	v_max_f32_e32 v160, v160, v161
	v_add_f32_e32 v161, 0x41000000, v139
	v_cmp_gt_f32_e32 vcc, v160, v161
	s_cbranch_vccz .LBB0_565
	v_max_f32_e32 v160, v160, v160
	v_max_f32_e32 v161, v139, v139
	v_max_f32_e32 v161, v161, v160
	v_sub_f32_e32 v139, v139, v161
	v_exp_f32_e32 v160, v139
	v_mov_b32_e32 v139, v161
	v_mul_f32_e32 v141, v141, v160
	v_pk_mul_f32 v[76:77], v[76:77], v[160:161] op_sel_hi:[1,0]
	v_pk_mul_f32 v[74:75], v[74:75], v[160:161] op_sel_hi:[1,0]
	v_pk_mul_f32 v[56:57], v[56:57], v[160:161] op_sel_hi:[1,0]
	v_pk_mul_f32 v[54:55], v[54:55], v[160:161] op_sel_hi:[1,0]
	v_pk_mul_f32 v[52:53], v[52:53], v[160:161] op_sel_hi:[1,0]
	v_pk_mul_f32 v[50:51], v[50:51], v[160:161] op_sel_hi:[1,0]
	v_pk_mul_f32 v[48:49], v[48:49], v[160:161] op_sel_hi:[1,0]
	v_pk_mul_f32 v[46:47], v[46:47], v[160:161] op_sel_hi:[1,0]
	v_xor_b32_e32 v160, 0x80000000, v161
	s_branch .LBB0_566

.LBB0_566:
	v_add_f32_e32 v144, v145, v144
	v_max3_f32 v145, v90, s18, v91
	v_max3_f32 v145, v145, v92, v93
	v_max3_f32 v145, v145, v82, v83
	v_max3_f32 v145, v145, v84, v85
	v_max3_f32 v145, v145, v86, v87
	v_max3_f32 v145, v145, v88, v89
	v_max3_f32 v145, v145, v78, v79
	v_add_f32_e32 v144, v147, v144
	v_max3_f32 v145, v145, v80, v81
	v_add_f32_e32 v144, v149, v144
	v_mul_f32_e32 v145, 0x3e16c740, v145
	v_add_f32_e32 v144, v153, v144
	v_mov_b32_e32 v147, v145
	s_nop 1
	v_permlane16_swap_b32_e32 v147, v145
	v_add_f32_e32 v144, v156, v144
	v_add_f32_e32 v144, v157, v144
	v_add_f32_e32 v144, v158, v144
	v_add_f32_e32 v144, v159, v144
	v_add_f32_e32 v144, v146, v144
	v_max_f32_e32 v146, v147, v147
	v_add_f32_e32 v144, v148, v144
	v_max_f32_e32 v145, v145, v146
	v_add_f32_e32 v144, v150, v144
	v_mov_b32_e32 v146, v145
	s_nop 1
	v_permlane32_swap_b32_e32 v146, v145
	v_add_f32_e32 v144, v154, v144
	v_add_f32_e32 v144, v151, v144
	v_add_f32_e32 v144, v152, v144
	v_add_f32_e32 v144, v155, v144
	v_add_f32_e32 v140, v140, v144
	v_max_f32_e32 v144, v146, v146
	v_max_f32_e32 v144, v145, v144
	v_add_f32_e32 v145, 0x41000000, v138
	v_cmp_gt_f32_e32 vcc, v144, v145
	s_cbranch_vccz .LBB0_568
	v_max_f32_e32 v144, v144, v144
	v_max_f32_e32 v145, v138, v138
	v_max_f32_e32 v145, v145, v144
	v_sub_f32_e32 v138, v138, v145
	v_exp_f32_e32 v138, v138
	v_xor_b32_e32 v144, 0x80000000, v145
	v_mul_f32_e32 v140, v140, v138
	v_pk_mul_f32 v[60:61], v[60:61], v[138:139] op_sel_hi:[1,0]
	v_pk_mul_f32 v[58:59], v[58:59], v[138:139] op_sel_hi:[1,0]
	v_pk_mul_f32 v[72:73], v[72:73], v[138:139] op_sel_hi:[1,0]
	v_pk_mul_f32 v[70:71], v[70:71], v[138:139] op_sel_hi:[1,0]
	v_pk_mul_f32 v[68:69], v[68:69], v[138:139] op_sel_hi:[1,0]
	v_pk_mul_f32 v[66:67], v[66:67], v[138:139] op_sel_hi:[1,0]
	v_pk_mul_f32 v[64:65], v[64:65], v[138:139] op_sel_hi:[1,0]
	v_pk_mul_f32 v[62:63], v[62:63], v[138:139] op_sel_hi:[1,0]
	v_mov_b32_e32 v138, v145
	s_branch .LBB0_569
